# attention big-unit split 32/34 key tiles between the partial producer and the finishing workgroup (was 33/33)
# baseline (speedup 1.0000x reference)
.LBB0_389:
	s_ashr_i32 s0, s33, 3
	s_cmp_lt_i32 s0, 16
	s_cselect_b64 s[14:15], -1, 0
	v_cndmask_b32_e64 v0, 0, 1, s[14:15]
	v_readlane_b32 s1, v255, 14
	s_cmp_gt_i32 s0, 15
	s_cselect_b64 s[72:73], -1, 0
	v_cmp_eq_u32_e32 vcc, s1, v0
	s_cbranch_vccnz .LBB0_388
	v_writelane_b32 v255, s3, 21
	s_and_b32 s1, s3, 3
	v_writelane_b32 v255, s2, 22
	s_bfe_u32 s2, s2, 0x10002
	s_lshl_b32 s4, s1, 22
	s_lshl_b32 s5, s2, 14
	s_lshl_b32 s7, s1, 8
	s_and_b32 s8, s33, 3
	s_and_b32 s1, s33, 7
	s_bfe_u32 s10, s33, 0x40003
	s_mul_i32 s6, s2, 0x2800000
	s_and_b64 s[2:3], s[14:15], exec
	s_cselect_b32 s3, 1, 2
	s_cmp_gt_i32 s0, 15
	s_cselect_b64 s[20:21], -1, 0
	s_lshl_b32 s0, s1, 4
	s_or_b32 s0, s10, s0
	s_lshl_b32 s78, s10, 1
	s_xor_b32 s11, s0, 15
	s_sub_i32 s2, 64, s78
	s_and_b64 s[0:1], s[14:15], exec
	s_cselect_b32 s67, 32, s2
	s_lshl_b32 s0, s33, 11
	v_writelane_b32 v255, s20, 23
	s_and_b32 s79, s0, 0x2000
	s_add_i32 s78, s78, 2
	v_writelane_b32 v255, s21, 24
	s_mul_i32 s0, s79, 0x1400
	v_readlane_b32 s20, v254, 45
	v_readlane_b32 s21, v254, 46
	s_add_u32 s0, s20, s0
	s_addc_u32 s1, s21, 0
	s_lshl_b32 s2, s8, 22
	s_add_u32 s13, s74, s2
	s_addc_u32 s17, s75, 0
	s_lshl_b32 s18, s8, 8
	s_add_u32 s0, s0, s18
	s_addc_u32 s1, s1, 0
	v_writelane_b32 v255, s33, 25
	s_add_u32 s33, s0, 0x1000
	s_addc_u32 s2, s1, 0
	s_lshl_b32 s0, s79, 1
	s_add_u32 s0, s13, s0
	s_addc_u32 s1, s17, 0
	s_add_u32 s17, s0, 0xb600000
	s_addc_u32 s71, s1, 0
	s_lshl_b32 s0, s11, 8
	v_readlane_b32 s1, v255, 8
	s_add_u32 s60, s1, s0
	v_readlane_b32 s0, v255, 9
	s_addc_u32 s61, s0, 0
	s_lshl_b32 s0, s11, 3
	v_readlane_b32 s1, v254, 25
	v_readlane_b32 s28, v254, 0
	s_add_i32 s8, s0, s1
	v_readlane_b32 s30, v254, 2
	v_readlane_b32 s31, v254, 3
	s_lshl_b64 s[0:1], s[8:9], 15
	s_mov_b64 s[26:27], s[30:31]
	s_add_u32 s62, s26, s0
	s_addc_u32 s63, s27, s1
	s_lshl_b64 s[0:1], s[8:9], 9
	v_readlane_b32 s8, v255, 6
	s_add_u32 s64, s8, s0
	v_readlane_b32 s0, v255, 7
	s_addc_u32 s65, s0, s1
	s_lshl_b32 s70, s10, 8
	s_xor_b32 s13, s70, 0x1f00
	s_add_u32 s68, s20, s18
	s_addc_u32 s69, s21, 0
	v_readlane_b32 s0, v255, 4
	s_add_u32 s0, s0, s18
	s_mov_b32 s27, 0
	v_writelane_b32 v255, s0, 26
	v_readlane_b32 s29, v254, 1
	v_readlane_b32 s0, v255, 5
	s_addc_u32 s0, s0, 0
	s_nop 0
	v_writelane_b32 v255, s0, 27
	s_or_b32 s0, s4, s5
	s_add_u32 s18, s0, 0xb600100
	s_addc_u32 s0, 0, 0
	v_writelane_b32 v255, s0, 28
	s_or_b32 s0, s6, s7
	s_or_b32 s26, s0, 0x46a1000
	s_branch .LBB0_392

.LBB0_392:
	s_cmp_eq_u32 s27, 0
	v_readlane_b32 s4, v255, 23
	s_cselect_b64 s[0:1], -1, 0
	v_readlane_b32 s5, v255, 24
	s_and_b64 s[4:5], s[4:5], s[0:1]
	s_or_b64 s[0:1], s[14:15], s[0:1]
	s_and_b64 s[0:1], s[0:1], exec
	s_cselect_b32 s29, 0, 32
	s_and_b64 s[0:1], s[4:5], exec
	s_cselect_b32 s31, s70, s13
	s_cselect_b32 s28, 0, s3
	s_cselect_b32 s30, s78, s67
	s_add_i32 s31, s31, s44
	s_add_i32 s8, s31, s79
	s_and_b64 vcc, exec, s[52:53]
	s_mul_i32 s20, s29, 0xa0000
	s_cbranch_vccz .LBB0_405
	v_mbcnt_lo_u32_b32 v192, -1, 0
	v_mbcnt_hi_u32_b32 v192, -1, v192
	v_mov_b64_e32 v[2:3], s[68:69]
	v_and_b32_e32 v7, 31, v192
	v_ashrrev_i32_e32 v214, 5, v192
	v_or_b32_e32 v0, s8, v7
	v_lshlrev_b32_e32 v194, 3, v214
	v_mad_u64_u32 v[2:3], s[0:1], v0, s80, v[2:3]
	v_ashrrev_i32_e32 v195, 31, v194
	v_lshl_add_u64 v[2:3], v[194:195], 1, v[2:3]
	global_load_dwordx4 v[160:163], v[2:3], off offset:3072
	global_load_dwordx4 v[164:167], v[2:3], off offset:3104
	global_load_dwordx4 v[168:171], v[2:3], off offset:3136
	global_load_dwordx4 v[172:175], v[2:3], off offset:3168
	global_load_dwordx4 v[176:179], v[2:3], off offset:3200
	global_load_dwordx4 v[180:183], v[2:3], off offset:3232
	global_load_dwordx4 v[184:187], v[2:3], off offset:3264
	global_load_dwordx4 v[188:191], v[2:3], off offset:3296
	v_ashrrev_i32_e32 v2, 4, v192
	v_add_u32_e32 v6, s12, v2
	v_add_u32_e32 v9, 4, v6
	v_xor_b32_e32 v4, v9, v192
	v_lshlrev_b32_e32 v4, 3, v4
	v_xor_b32_e32 v0, v2, v192
	v_and_b32_e32 v4, 0x78, v4
	v_lshlrev_b32_e32 v0, 3, v0
	v_lshl_or_b32 v12, v9, 14, v4
	v_add_u32_e32 v9, 8, v6
	v_mul_lo_u32 v5, v6, s81
	v_and_b32_e32 v3, 0x78, v0
	v_xor_b32_e32 v11, v9, v192
	v_or_b32_e32 v0, v3, v5
	v_or_b32_e32 v10, v5, v4
	v_add_u32_e32 v13, 0x5000, v5
	v_lshlrev_b32_e32 v5, 3, v11
	v_and_b32_e32 v5, 0x78, v5
	v_lshl_or_b32 v16, v9, 14, v5
	v_add_u32_e32 v9, 12, v6
	v_lshl_or_b32 v8, v6, 14, v3
	v_xor_b32_e32 v6, v9, v192
	s_add_u32 s4, s33, s20
	v_lshlrev_b32_e32 v6, 3, v6
	s_addc_u32 s5, s2, 0
	s_lshl_b32 s0, s29, 8
	v_and_b32_e32 v6, 0x78, v6
	s_add_u32 s6, s17, s0
	s_mov_b32 m0, s41
	v_or_b32_e32 v11, v13, v6
	v_lshl_or_b32 v20, v9, 14, v6
	s_addc_u32 s7, s71, 0
	v_lshl_add_u64 v[22:23], v[0:1], 1, s[4:5]
	v_mov_b32_e32 v9, v1
	v_add_u32_e32 v10, 0x2800, v10
	v_add_u32_e32 v18, 0x2800, v11
	global_load_lds_dwordx4 v[22:23], off
	v_lshl_add_u64 v[8:9], v[8:9], 1, s[6:7]
	s_mov_b32 m0, s19
	v_mov_b32_e32 v11, v1
	v_or_b32_e32 v14, v5, v13
	global_load_lds_dwordx4 v[8:9], off
	v_lshl_add_u64 v[8:9], v[10:11], 1, s[4:5]
	s_mov_b32 m0, s43
	v_mov_b32_e32 v13, v1
	global_load_lds_dwordx4 v[8:9], off
	v_lshl_add_u64 v[8:9], v[12:13], 1, s[6:7]
	s_mov_b32 m0, s37
	v_mov_b32_e32 v15, v1
	global_load_lds_dwordx4 v[8:9], off
	v_lshl_add_u64 v[8:9], v[14:15], 1, s[4:5]
	s_mov_b32 m0, s38
	v_mov_b32_e32 v17, v1
	global_load_lds_dwordx4 v[8:9], off
	v_lshl_add_u64 v[8:9], v[16:17], 1, s[6:7]
	s_mov_b32 m0, s39
	v_mov_b32_e32 v19, v1
	global_load_lds_dwordx4 v[8:9], off
	v_lshl_add_u64 v[8:9], v[18:19], 1, s[4:5]
	s_mov_b32 m0, s42
	v_mov_b32_e32 v21, v1
	global_load_lds_dwordx4 v[8:9], off
	v_lshl_add_u64 v[8:9], v[20:21], 1, s[6:7]
	s_mov_b32 m0, s66
	s_cmp_ge_u32 s29, s30
	global_load_lds_dwordx4 v[8:9], off
	s_cbranch_scc1 .LBB0_406
	v_lshlrev_b32_e32 v8, 1, v7
	v_lshrrev_b32_e32 v9, 1, v192
	v_and_b32_e32 v0, 19, v192
	v_and_b32_e32 v8, 8, v8
	v_and_b32_e32 v9, 4, v9
	v_or3_b32 v0, v9, v0, v8
	v_or_b32_e32 v193, s31, v7
	v_lshlrev_b32_e32 v195, 8, v7
	v_bitop3_b32 v7, v0, v214, 15 bitop3:0x6c
	v_lshlrev_b32_e32 v216, 4, v7
	v_add_u32_e32 v7, 2, v214
	v_bitop3_b32 v8, v0, v7, 15 bitop3:0x6c
	v_lshlrev_b32_e32 v217, 4, v8
	v_add_u32_e32 v8, 4, v214
	v_bitop3_b32 v9, v0, v8, 15 bitop3:0x6c
	v_lshlrev_b32_e32 v218, 4, v9
	v_add_u32_e32 v9, 6, v214
	v_bitop3_b32 v10, v0, v9, 15 bitop3:0x6c
	v_lshlrev_b32_e32 v219, 4, v10
	v_add_u32_e32 v10, 8, v214
	v_bitop3_b32 v11, v0, v10, 15 bitop3:0x6c
	v_lshlrev_b32_e32 v220, 4, v11
	v_add_u32_e32 v11, 10, v214
	v_bitop3_b32 v12, v0, v11, 15 bitop3:0x6c
	v_lshlrev_b32_e32 v221, 4, v12
	v_add_u32_e32 v12, 12, v214
	v_bitop3_b32 v13, v0, v12, 15 bitop3:0x6c
	v_lshlrev_b32_e32 v222, 4, v13
	v_add_u32_e32 v13, 14, v214
	v_lshlrev_b32_e32 v215, 8, v0
	v_bitop3_b32 v0, v0, v13, 15 bitop3:0x6c
	v_lshlrev_b32_e32 v223, 4, v0
	v_bitop3_b32 v0, v214, v192, 15 bitop3:0x78
	v_lshlrev_b32_e32 v224, 4, v0
	v_bitop3_b32 v0, v7, v192, 15 bitop3:0x78
	v_lshlrev_b32_e32 v225, 4, v0
	v_bitop3_b32 v0, v8, v192, 15 bitop3:0x78
	v_lshlrev_b32_e32 v226, 4, v0
	v_bitop3_b32 v0, v9, v192, 15 bitop3:0x78
	v_lshlrev_b32_e32 v227, 4, v0
	v_bitop3_b32 v0, v10, v192, 15 bitop3:0x78
	s_lshl_b32 s1, s29, 7
	v_lshlrev_b32_e32 v228, 4, v0
	v_bitop3_b32 v0, v11, v192, 15 bitop3:0x78
	s_or_b32 s21, s31, 31
	v_lshlrev_b32_e32 v229, 4, v0
	v_bitop3_b32 v0, v12, v192, 15 bitop3:0x78
	s_add_i32 s34, s1, 0x7f
	v_lshlrev_b32_e32 v230, 4, v0
	v_bitop3_b32 v0, v13, v192, 15 bitop3:0x78
	s_add_u32 s0, s18, s0
	v_readlane_b32 s1, v255, 28
	v_lshlrev_b32_e32 v7, 14, v2
	v_lshlrev_b32_e32 v231, 4, v0
	s_addc_u32 s1, s1, 0
	v_add3_u32 v0, s36, v7, v3
	v_lshl_add_u64 v[198:199], v[0:1], 1, s[0:1]
	v_add3_u32 v0, s54, v7, v4
	v_lshl_add_u64 v[200:201], v[0:1], 1, s[0:1]
	v_add3_u32 v0, s55, v7, v5
	v_lshl_add_u64 v[202:203], v[0:1], 1, s[0:1]
	v_add3_u32 v0, s56, v7, v6
	v_lshl_add_u64 v[204:205], v[0:1], 1, s[0:1]
	s_add_u32 s0, s26, s20
	v_mul_lo_u32 v2, v2, s81
	s_addc_u32 s1, 0, 0
	v_add3_u32 v0, s57, v2, v3
	v_lshl_add_u64 v[206:207], v[0:1], 1, s[0:1]
	v_add3_u32 v0, s58, v2, v4
	v_lshl_add_u64 v[208:209], v[0:1], 1, s[0:1]
	v_add3_u32 v0, s59, v2, v5
	v_readlane_b32 s4, v255, 11
	v_lshl_add_u64 v[210:211], v[0:1], 1, s[0:1]
	v_mov_b32_e32 v14, v1
	v_add3_u32 v0, s4, v2, v6
	v_mov_b32_e32 v15, v1
	v_lshl_add_u64 v[212:213], v[0:1], 1, s[0:1]
	v_mov_b32_e32 v0, v1
	v_mov_b32_e32 v2, v1
	v_mov_b32_e32 v3, v1
	v_mov_b32_e32 v4, v1
	v_mov_b32_e32 v5, v1
	v_mov_b32_e32 v6, v1
	v_mov_b32_e32 v7, v1
	v_mov_b32_e32 v8, v1
	v_mov_b32_e32 v9, v1
	v_mov_b32_e32 v10, v1
	v_mov_b32_e32 v11, v1
	v_mov_b32_e32 v12, v1
	v_mov_b32_e32 v13, v1
	v_mov_b64_e32 v[142:143], v[14:15]
	v_mov_b64_e32 v[126:127], v[14:15]
	v_mov_b64_e32 v[110:111], v[14:15]
	v_mov_b64_e32 v[94:95], v[14:15]
	v_mov_b64_e32 v[78:79], v[14:15]
	v_mov_b64_e32 v[62:63], v[14:15]
	v_mov_b64_e32 v[46:47], v[14:15]
	v_mov_b64_e32 v[30:31], v[14:15]
	v_add_u32_e32 v235, -16, v193
	v_subrev_u32_e32 v236, 17, v193
	v_subrev_u32_e32 v237, 18, v193
	v_subrev_u32_e32 v238, 19, v193
	v_subrev_u32_e32 v239, 20, v193
	v_subrev_u32_e32 v240, 21, v193
	v_subrev_u32_e32 v241, 22, v193
	v_subrev_u32_e32 v242, 23, v193
	s_mov_b32 s35, 0
	v_mov_b32_e32 v197, 0
	v_mov_b64_e32 v[140:141], v[12:13]
	v_mov_b64_e32 v[138:139], v[10:11]
	v_mov_b64_e32 v[136:137], v[8:9]
	v_mov_b64_e32 v[134:135], v[6:7]
	v_mov_b64_e32 v[132:133], v[4:5]
	v_mov_b64_e32 v[130:131], v[2:3]
	v_mov_b64_e32 v[128:129], v[0:1]
	v_mov_b64_e32 v[124:125], v[12:13]
	v_mov_b64_e32 v[122:123], v[10:11]
	v_mov_b64_e32 v[120:121], v[8:9]
	v_mov_b64_e32 v[118:119], v[6:7]
	v_mov_b64_e32 v[116:117], v[4:5]
	v_mov_b64_e32 v[114:115], v[2:3]
	v_mov_b64_e32 v[112:113], v[0:1]
	v_mov_b64_e32 v[108:109], v[12:13]
	v_mov_b64_e32 v[106:107], v[10:11]
	v_mov_b64_e32 v[104:105], v[8:9]
	v_mov_b64_e32 v[102:103], v[6:7]
	v_mov_b64_e32 v[100:101], v[4:5]
	v_mov_b64_e32 v[98:99], v[2:3]
	v_mov_b64_e32 v[96:97], v[0:1]
	v_mov_b64_e32 v[92:93], v[12:13]
	v_mov_b64_e32 v[90:91], v[10:11]
	v_mov_b64_e32 v[88:89], v[8:9]
	v_mov_b64_e32 v[86:87], v[6:7]
	v_mov_b64_e32 v[84:85], v[4:5]
	v_mov_b64_e32 v[82:83], v[2:3]
	v_mov_b64_e32 v[80:81], v[0:1]
	v_mov_b64_e32 v[76:77], v[12:13]
	v_mov_b64_e32 v[74:75], v[10:11]
	v_mov_b64_e32 v[72:73], v[8:9]
	v_mov_b64_e32 v[70:71], v[6:7]
	v_mov_b64_e32 v[68:69], v[4:5]
	v_mov_b64_e32 v[66:67], v[2:3]
	v_mov_b64_e32 v[64:65], v[0:1]
	v_mov_b64_e32 v[60:61], v[12:13]
	v_mov_b64_e32 v[58:59], v[10:11]
	v_mov_b64_e32 v[56:57], v[8:9]
	v_mov_b64_e32 v[54:55], v[6:7]
	v_mov_b64_e32 v[52:53], v[4:5]
	v_mov_b64_e32 v[50:51], v[2:3]
	v_mov_b64_e32 v[48:49], v[0:1]
	v_mov_b64_e32 v[44:45], v[12:13]
	v_mov_b64_e32 v[42:43], v[10:11]
	v_mov_b64_e32 v[40:41], v[8:9]
	v_mov_b64_e32 v[38:39], v[6:7]
	v_mov_b64_e32 v[36:37], v[4:5]
	v_mov_b64_e32 v[34:35], v[2:3]
	v_mov_b64_e32 v[32:33], v[0:1]
	v_mov_b64_e32 v[28:29], v[12:13]
	v_mov_b64_e32 v[26:27], v[10:11]
	v_mov_b64_e32 v[24:25], v[8:9]
	v_mov_b64_e32 v[22:23], v[6:7]
	v_mov_b64_e32 v[20:21], v[4:5]
	v_mov_b64_e32 v[18:19], v[2:3]
	v_mov_b64_e32 v[16:17], v[0:1]
	v_mov_b32_e32 v196, 0
	s_waitcnt vmcnt(0)
	s_branch .LBB0_396
